# GDN derive stage: conv4 LDS reads batched per block with counted waits
# baseline (speedup 1.0000x reference)
; #define LAS __attribute__((address_space(3)))
; DI float siluf_(float x) { return x * frcp(1.f + __expf(-x)); }
; DI f32x4 gd_conv4(const LAS float* CW, const LAS float* RAW, int dt, int cc) {
;     f32x4 a = {0.f, 0.f, 0.f, 0.f};
; #pragma unroll
;     for (int j = 0; j < 4; ++j) a += *(const LAS f32x4*)(CW + j * 320 + cc) * *(const LAS f32x4*)(RAW + (dt + j) * 320 + cc);
; #pragma unroll
;     for (int i = 0; i < 4; ++i) a[i] = siluf_(a[i]);
;     return a;
; }
.LBB0_898:
	s_or_b64 exec, exec, s[34:35]
	s_waitcnt lgkmcnt(0)
	s_barrier
	ds_read_b128 v[208:211], v111
	ds_read_b128 v[212:215], v162
	ds_read_b128 v[216:219], v111 offset:1280
	ds_read_b128 v[220:223], v162 offset:1280
	ds_read_b128 v[224:227], v111 offset:2560
	ds_read_b128 v[228:231], v162 offset:2560
	ds_read_b128 v[72:75], v111 offset:3840
	ds_read_b128 v[76:79], v162 offset:3840
	s_waitcnt lgkmcnt(6)
	v_pk_fma_f32 v[80:81], v[210:211], v[214:215], 0 op_sel_hi:[1,1,0]
	v_pk_fma_f32 v[100:101], v[208:209], v[212:213], 0 op_sel_hi:[1,1,0]
	s_waitcnt lgkmcnt(4)
	v_pk_fma_f32 v[80:81], v[218:219], v[222:223], v[80:81]
	v_pk_fma_f32 v[100:101], v[216:217], v[220:221], v[100:101]
	s_waitcnt lgkmcnt(2)
	v_pk_fma_f32 v[80:81], v[226:227], v[230:231], v[80:81]
	v_pk_fma_f32 v[100:101], v[224:225], v[228:229], v[100:101]
	s_waitcnt lgkmcnt(0)
	v_pk_fma_f32 v[72:73], v[72:73], v[76:77], v[100:101]
	s_nop 0
	v_mul_f32_e32 v76, 0xbfb8aa3b, v72
	v_mul_f32_e32 v77, 0xbfb8aa3b, v73
	v_exp_f32_e32 v76, v76
	v_exp_f32_e32 v77, v77
	v_pk_fma_f32 v[74:75], v[74:75], v[78:79], v[80:81]
	v_add_f32_e32 v76, 1.0, v76
	v_add_f32_e32 v77, 1.0, v77
	v_rcp_f32_e32 v76, v76
	v_rcp_f32_e32 v77, v77
	s_nop 0
	v_pk_mul_f32 v[72:73], v[72:73], v[76:77]
	v_mul_f32_e32 v76, 0xbfb8aa3b, v74
	v_mul_f32_e32 v77, 0xbfb8aa3b, v75
	v_exp_f32_e32 v76, v76
	v_exp_f32_e32 v77, v77
	v_add_f32_e32 v76, 1.0, v76
	v_add_f32_e32 v77, 1.0, v77
	v_rcp_f32_e32 v76, v76
	v_rcp_f32_e32 v77, v77
	s_nop 0
	v_pk_mul_f32 v[74:75], v[74:75], v[76:77]
	ds_read_b128 v[208:211], v112
	ds_read_b128 v[212:215], v113
	ds_read_b128 v[216:219], v112 offset:1280
	ds_read_b128 v[220:223], v113 offset:1280
	ds_read_b128 v[224:227], v112 offset:2560
	ds_read_b128 v[228:231], v113 offset:2560
	ds_read_b128 v[76:79], v112 offset:3840
	ds_read_b128 v[100:103], v113 offset:3840
	s_waitcnt lgkmcnt(6)
	v_pk_fma_f32 v[80:81], v[210:211], v[214:215], 0 op_sel_hi:[1,1,0]
	v_pk_fma_f32 v[104:105], v[208:209], v[212:213], 0 op_sel_hi:[1,1,0]
	s_waitcnt lgkmcnt(4)
	v_pk_fma_f32 v[80:81], v[218:219], v[222:223], v[80:81]
	v_pk_fma_f32 v[104:105], v[216:217], v[220:221], v[104:105]
	s_waitcnt lgkmcnt(2)
	v_pk_fma_f32 v[80:81], v[226:227], v[230:231], v[80:81]
	v_pk_fma_f32 v[104:105], v[224:225], v[228:229], v[104:105]
	s_waitcnt lgkmcnt(0)
	v_pk_fma_f32 v[76:77], v[76:77], v[100:101], v[104:105]
	v_pk_fma_f32 v[78:79], v[78:79], v[102:103], v[80:81]
	v_mul_f32_e32 v80, 0xbfb8aa3b, v76
	v_mul_f32_e32 v81, 0xbfb8aa3b, v77
	v_exp_f32_e32 v80, v80
	v_exp_f32_e32 v81, v81
	ds_read_b128 v[208:211], v114
	ds_read_b128 v[212:215], v115
	ds_read_b128 v[216:219], v114 offset:1280
	ds_read_b128 v[220:223], v115 offset:1280
	ds_read_b128 v[224:227], v114 offset:2560
	ds_read_b128 v[228:231], v115 offset:2560
	ds_read_b128 v[100:103], v114 offset:3840
	ds_read_b128 v[190:193], v115 offset:3840
	v_add_f32_e32 v80, 1.0, v80
	v_add_f32_e32 v81, 1.0, v81
	v_rcp_f32_e32 v80, v80
	v_rcp_f32_e32 v81, v81
	s_waitcnt lgkmcnt(6)
	v_pk_fma_f32 v[104:105], v[208:209], v[212:213], 0 op_sel_hi:[1,1,0]
	v_pk_mul_f32 v[76:77], v[76:77], v[80:81]
	v_mul_f32_e32 v80, 0xbfb8aa3b, v78
	v_mul_f32_e32 v81, 0xbfb8aa3b, v79
	v_exp_f32_e32 v80, v80
	v_exp_f32_e32 v81, v81
	v_add_f32_e32 v80, 1.0, v80
	v_add_f32_e32 v81, 1.0, v81
	v_rcp_f32_e32 v80, v80
	v_rcp_f32_e32 v81, v81
	s_nop 0
	v_pk_mul_f32 v[78:79], v[78:79], v[80:81]
	v_pk_fma_f32 v[80:81], v[210:211], v[214:215], 0 op_sel_hi:[1,1,0]
	s_waitcnt lgkmcnt(4)
	v_pk_fma_f32 v[80:81], v[218:219], v[222:223], v[80:81]
	v_pk_fma_f32 v[104:105], v[216:217], v[220:221], v[104:105]
	s_waitcnt lgkmcnt(2)
	v_pk_fma_f32 v[80:81], v[226:227], v[230:231], v[80:81]
	v_pk_fma_f32 v[104:105], v[224:225], v[228:229], v[104:105]
	s_waitcnt lgkmcnt(0)
	v_pk_fma_f32 v[102:103], v[102:103], v[192:193], v[80:81]
	v_pk_fma_f32 v[80:81], v[100:101], v[190:191], v[104:105]
	s_nop 0
	v_mul_f32_e32 v100, 0xbfb8aa3b, v80
	v_mul_f32_e32 v101, 0xbfb8aa3b, v81
	v_exp_f32_e32 v100, v100
	v_exp_f32_e32 v101, v101
	v_add_f32_e32 v100, 1.0, v100
	v_add_f32_e32 v101, 1.0, v101
	v_rcp_f32_e32 v100, v100
	v_rcp_f32_e32 v101, v101
	s_nop 0
	v_pk_mul_f32 v[80:81], v[80:81], v[100:101]
	v_mul_f32_e32 v100, 0xbfb8aa3b, v102
	v_mul_f32_e32 v101, 0xbfb8aa3b, v103
	v_exp_f32_e32 v100, v100
	v_exp_f32_e32 v101, v101
	v_add_f32_e32 v100, 1.0, v100
	v_add_f32_e32 v101, 1.0, v101
	v_rcp_f32_e32 v100, v100
	v_rcp_f32_e32 v101, v101
	s_nop 0
	v_pk_mul_f32 v[100:101], v[102:103], v[100:101]
	ds_read_b128 v[208:211], v116
	ds_read_b128 v[212:215], v117
	ds_read_b128 v[216:219], v116 offset:1280
	ds_read_b128 v[220:223], v117 offset:1280
	ds_read_b128 v[224:227], v116 offset:2560
	ds_read_b128 v[228:231], v117 offset:2560
	ds_read_b128 v[102:105], v116 offset:3840
	ds_read_b128 v[190:193], v117 offset:3840
	s_waitcnt lgkmcnt(6)
	v_pk_fma_f32 v[130:131], v[210:211], v[214:215], 0 op_sel_hi:[1,1,0]
	v_pk_fma_f32 v[194:195], v[208:209], v[212:213], 0 op_sel_hi:[1,1,0]
	s_waitcnt lgkmcnt(4)
	v_pk_fma_f32 v[130:131], v[218:219], v[222:223], v[130:131]
	v_pk_fma_f32 v[194:195], v[216:217], v[220:221], v[194:195]
	s_waitcnt lgkmcnt(2)
	v_pk_fma_f32 v[130:131], v[226:227], v[230:231], v[130:131]
	v_pk_fma_f32 v[194:195], v[224:225], v[228:229], v[194:195]
	s_waitcnt lgkmcnt(0)
	v_pk_fma_f32 v[102:103], v[102:103], v[190:191], v[194:195]
	s_nop 0
	v_mul_f32_e32 v106, 0xbfb8aa3b, v102
	v_exp_f32_e32 v106, v106
	v_pk_fma_f32 v[104:105], v[104:105], v[192:193], v[130:131]
	ds_read_b128 v[208:211], v118
	ds_read_b128 v[212:215], v119
	ds_read_b128 v[216:219], v118 offset:1280
	ds_read_b128 v[220:223], v119 offset:1280
	ds_read_b128 v[224:227], v118 offset:2560
	ds_read_b128 v[228:231], v119 offset:2560
	ds_read_b128 v[190:193], v118 offset:3840
	ds_read_b128 v[194:197], v119 offset:3840
	v_add_f32_e32 v106, 1.0, v106
	v_rcp_f32_e32 v130, v106
	v_mul_f32_e32 v106, 0xbfb8aa3b, v103
	v_exp_f32_e32 v106, v106
	s_waitcnt lgkmcnt(6)
	v_pk_fma_f32 v[198:199], v[208:209], v[212:213], 0 op_sel_hi:[1,1,0]
	v_add_f32_e32 v106, 1.0, v106
	v_rcp_f32_e32 v131, v106
	v_mul_f32_e32 v106, 0xbfb8aa3b, v104
	v_exp_f32_e32 v106, v106
	v_pk_mul_f32 v[102:103], v[102:103], v[130:131]
	v_add_f32_e32 v106, 1.0, v106
	v_rcp_f32_e32 v130, v106
	v_mul_f32_e32 v106, 0xbfb8aa3b, v105
	v_exp_f32_e32 v106, v106
	s_nop 0
	v_add_f32_e32 v106, 1.0, v106
	v_rcp_f32_e32 v131, v106
	s_nop 0
	v_pk_mul_f32 v[104:105], v[104:105], v[130:131]
	v_pk_fma_f32 v[130:131], v[210:211], v[214:215], 0 op_sel_hi:[1,1,0]
	s_waitcnt lgkmcnt(4)
	v_pk_fma_f32 v[130:131], v[218:219], v[222:223], v[130:131]
	v_pk_fma_f32 v[198:199], v[216:217], v[220:221], v[198:199]
	s_waitcnt lgkmcnt(2)
	v_pk_fma_f32 v[130:131], v[226:227], v[230:231], v[130:131]
	v_pk_fma_f32 v[198:199], v[224:225], v[228:229], v[198:199]
	s_waitcnt lgkmcnt(0)
	v_pk_fma_f32 v[190:191], v[190:191], v[194:195], v[198:199]
	s_nop 0
	v_mul_f32_e32 v106, 0xbfb8aa3b, v190
	v_exp_f32_e32 v106, v106
	v_pk_fma_f32 v[130:131], v[192:193], v[196:197], v[130:131]
	v_mov_b32_e32 v196, v75
	v_mov_b32_e32 v197, v79
	v_add_f32_e32 v106, 1.0, v106
	v_rcp_f32_e32 v194, v106
	v_mul_f32_e32 v106, 0xbfb8aa3b, v191
	v_exp_f32_e32 v106, v106
	v_pk_mul_f32 v[196:197], v[196:197], v[196:197]
	v_add_f32_e32 v106, 1.0, v106
	v_rcp_f32_e32 v195, v106
	v_mul_f32_e32 v106, 0xbfb8aa3b, v130
	v_exp_f32_e32 v106, v106
	v_pk_mul_f32 v[190:191], v[190:191], v[194:195]
	v_mov_b32_e32 v194, v73
	v_add_f32_e32 v106, 1.0, v106
	v_rcp_f32_e32 v192, v106
	v_mul_f32_e32 v106, 0xbfb8aa3b, v131
	v_exp_f32_e32 v106, v106
	v_mov_b32_e32 v195, v77
	v_pk_mul_f32 v[194:195], v[194:195], v[194:195]
	v_add_f32_e32 v106, 1.0, v106
	v_rcp_f32_e32 v193, v106
	s_nop 0
	v_pk_mul_f32 v[192:193], v[130:131], v[192:193]
	v_mov_b32_e32 v130, v72
	v_mov_b32_e32 v131, v76
	v_pk_fma_f32 v[130:131], v[130:131], v[130:131], v[194:195]
	v_mov_b32_e32 v194, v74
	v_mov_b32_e32 v195, v78
	v_pk_fma_f32 v[194:195], v[194:195], v[194:195], v[196:197]
	v_mov_b32_e32 v196, v101
	v_pk_add_f32 v[130:131], v[130:131], v[194:195]
	v_mov_b32_e32 v194, v81
	v_mov_b32_e32 v195, v103
	v_add_f32_e32 v106, v130, v131
	v_mov_b32_e32 v130, v80
	v_mov_b32_e32 v131, v102
	v_pk_mul_f32 v[194:195], v[194:195], v[194:195]
	v_mov_b32_e32 v197, v105
	v_pk_fma_f32 v[130:131], v[130:131], v[130:131], v[194:195]
	v_mov_b32_e32 v194, v100
	v_mov_b32_e32 v195, v104
	v_pk_mul_f32 v[196:197], v[196:197], v[196:197]
	v_add_f32_dpp v106, v106, v106 quad_perm:[1,0,3,2] row_mask:0xf bank_mask:0xf bound_ctrl:1
	v_pk_fma_f32 v[194:195], v[194:195], v[194:195], v[196:197]
	s_nop 0
	v_pk_add_f32 v[130:131], v[130:131], v[194:195]
	v_add_f32_dpp v106, v106, v106 quad_perm:[2,3,0,1] row_mask:0xf bank_mask:0xf bound_ctrl:1
	v_add_f32_e32 v128, v130, v131
	s_nop 0
	v_add_f32_dpp v106, v106, v106 row_half_mirror row_mask:0xf bank_mask:0xf bound_ctrl:1
	v_add_f32_dpp v128, v128, v128 quad_perm:[1,0,3,2] row_mask:0xf bank_mask:0xf bound_ctrl:1
	s_nop 0
	v_add_f32_dpp v106, v106, v106 row_ror:8 row_mask:0xf bank_mask:0xf bound_ctrl:1
	v_add_f32_dpp v128, v128, v128 quad_perm:[2,3,0,1] row_mask:0xf bank_mask:0xf bound_ctrl:1
	v_add_f32_e32 v106, 0x358637bd, v106
	v_rsq_f32_e32 v106, v106
	v_add_f32_dpp v128, v128, v128 row_half_mirror row_mask:0xf bank_mask:0xf bound_ctrl:1
	v_mul_f32_e32 v106, 0x3db504f3, v106
	s_nop 0
	v_add_f32_dpp v128, v128, v128 row_ror:8 row_mask:0xf bank_mask:0xf bound_ctrl:1
	v_add_f32_e32 v128, 0x358637bd, v128
	v_rsq_f32_e32 v128, v128
	v_pk_mul_f32 v[74:75], v[74:75], v[106:107] op_sel_hi:[1,0]
	v_pk_mul_f32 v[72:73], v[72:73], v[106:107] op_sel_hi:[1,0]
	v_pk_mul_f32 v[78:79], v[78:79], v[106:107] op_sel_hi:[1,0]
	v_pk_mul_f32 v[76:77], v[76:77], v[106:107] op_sel_hi:[1,0]
	ds_write_b128 v120, v[72:75]
	v_pk_mul_f32 v[196:197], v[100:101], v[128:129] op_sel_hi:[1,0]
	v_pk_mul_f32 v[194:195], v[80:81], v[128:129] op_sel_hi:[1,0]
	v_pk_mul_f32 v[104:105], v[104:105], v[128:129] op_sel_hi:[1,0]
	v_pk_mul_f32 v[102:103], v[102:103], v[128:129] op_sel_hi:[1,0]
	v_cvt_pk_bf16_f32 v72, v72, v73
	v_cvt_pk_bf16_f32 v73, v74, v75
	v_cvt_pk_bf16_f32 v74, v76, v77
	v_cvt_pk_bf16_f32 v75, v78, v79
	v_add_u32_e32 v80, s83, v122
	ds_write_b128 v120, v[76:79] offset:16
	ds_write_b128 v120, v[194:197] offset:16896
	ds_write_b128 v120, v[102:105] offset:16912
	ds_write_b128 v121, v[190:193] offset:33792
	v_cvt_pk_bf16_f32 v76, v194, v195
	v_cvt_pk_bf16_f32 v77, v196, v197
	v_cvt_pk_bf16_f32 v78, v102, v103
	v_cvt_pk_bf16_f32 v79, v104, v105
	ds_write_b128 v80, v[72:75]
	v_add_u32_e32 v72, s46, v122
	ds_write_b128 v72, v[76:79]
	s_and_saveexec_b64 s[48:49], s[6:7]
	s_cbranch_execz .LBB0_900
	ds_read_b32 v72, v124
	s_mov_b32 s0, 0xbfb8aa3b
	s_waitcnt lgkmcnt(0)
	v_add_f32_e32 v72, v107, v72
	v_mul_f32_e64 v73, |v72|, s0
	v_exp_f32_e32 v73, v73
	s_mov_b32 s0, 0x800000
	v_max_f32_e32 v72, 0, v72
	v_add_f32_e32 v73, 1.0, v73
	v_cmp_gt_f32_e32 vcc, s0, v73
	s_mov_b32 s0, 0x3f317217
	s_nop 0
	v_cndmask_b32_e64 v74, 0, 32, vcc
	v_ldexp_f32 v73, v73, v74
	v_log_f32_e32 v73, v73
	s_nop 0
	v_mul_f32_e32 v74, 0x3f317217, v73
	v_fma_f32 v74, v73, s0, -v74
	v_fmac_f32_e32 v74, 0x3377d1cf, v73
	s_mov_b32 s0, 0x7f800000
	v_fmac_f32_e32 v74, 0x3f317217, v73
	v_cmp_lt_f32_e64 s[34:35], |v73|, s0
	s_nop 1
	v_cndmask_b32_e64 v73, v73, v74, s[34:35]
	v_cndmask_b32_e32 v74, 0, v243, vcc
	v_sub_f32_e32 v73, v73, v74
	v_add_f32_e32 v72, v72, v73
	v_mul_f32_e64 v72, v72, -v110
	ds_write_b32 v163, v72 offset:41984
	ds_read_b32 v72, v123
	s_waitcnt lgkmcnt(0)
	v_mul_f32_e32 v72, 0xbfb8aa3b, v72
	v_exp_f32_e32 v72, v72
	s_nop 0
	v_add_f32_e32 v72, 1.0, v72
	v_rcp_f32_e32 v72, v72
	ds_write_b32 v163, v72 offset:41988
